# final-norm phase: all 13 loads of a row issued up front, stores follow (one store-drain per iteration instead of four)
# speedup vs baseline: 1.0088x; 1.0088x over previous
.LBB0_1633:
	global_load_dwordx4 v[8:11], v[6:7], off
	global_load_dwordx2 v[16:17], v[4:5], off sc0 sc1
	global_load_dwordx2 v[18:19], v[4:5], off offset:8 sc0 sc1
	global_load_dwordx4 v[12:15], v[2:3], off
	global_load_dwordx2 v[24:25], v[4:5], off offset:1024 sc0 sc1
	global_load_dwordx2 v[26:27], v[4:5], off offset:1032 sc0 sc1
	global_load_dwordx4 v[28:31], v[2:3], off offset:1024
	global_load_dwordx2 v[32:33], v[4:5], off offset:2048 sc0 sc1
	global_load_dwordx2 v[34:35], v[4:5], off offset:2056 sc0 sc1
	global_load_dwordx4 v[36:39], v[2:3], off offset:2048
	global_load_dwordx2 v[40:41], v[4:5], off offset:3072 sc0 sc1
	global_load_dwordx2 v[42:43], v[4:5], off offset:3080 sc0 sc1
	global_load_dwordx4 v[44:47], v[2:3], off offset:3072
	v_add_u32_e32 v0, s42, v0
	v_lshl_add_u64 v[6:7], v[6:7], 0, s[14:15]
	s_waitcnt vmcnt(12)
	v_mov_b32_e32 v20, v9
	v_mov_b32_e32 v21, v10
	v_mov_b32_e32 v9, v11
	v_pk_add_f32 v[8:9], v[20:21], v[8:9]
	s_nop 0
	v_add_f32_e32 v1, v8, v9
	v_fmamk_f32 v1, v1, 0x3a800000, v178
	v_mul_f32_e32 v8, 0x4b800000, v1
	v_cmp_gt_f32_e32 vcc, s16, v1
	s_nop 1
	v_cndmask_b32_e32 v1, v1, v8, vcc
	v_rsq_f32_e32 v1, v1
	s_nop 0
	v_mul_f32_e32 v8, 0x45800000, v1
	v_cndmask_b32_e32 v20, v1, v8, vcc
	s_waitcnt vmcnt(9)
	v_pk_mul_f32 v[16:17], v[20:21], v[16:17] op_sel_hi:[0,1]
	v_pk_mul_f32 v[18:19], v[20:21], v[18:19] op_sel_hi:[0,1]
	v_pk_mul_f32 v[16:17], v[12:13], v[16:17]
	v_pk_mul_f32 v[18:19], v[14:15], v[18:19]
	global_store_dwordx4 v[4:5], v[16:19], off
	s_waitcnt vmcnt(7)
	v_pk_mul_f32 v[24:25], v[20:21], v[24:25] op_sel_hi:[0,1]
	v_pk_mul_f32 v[26:27], v[20:21], v[26:27] op_sel_hi:[0,1]
	v_pk_mul_f32 v[24:25], v[28:29], v[24:25]
	v_pk_mul_f32 v[26:27], v[30:31], v[26:27]
	global_store_dwordx4 v[4:5], v[24:27], off offset:1024
	s_waitcnt vmcnt(5)
	v_pk_mul_f32 v[32:33], v[20:21], v[32:33] op_sel_hi:[0,1]
	v_pk_mul_f32 v[34:35], v[20:21], v[34:35] op_sel_hi:[0,1]
	v_pk_mul_f32 v[32:33], v[36:37], v[32:33]
	v_pk_mul_f32 v[34:35], v[38:39], v[34:35]
	global_store_dwordx4 v[4:5], v[32:35], off offset:2048
	s_waitcnt vmcnt(3)
	v_pk_mul_f32 v[40:41], v[20:21], v[40:41] op_sel_hi:[0,1]
	v_pk_mul_f32 v[42:43], v[20:21], v[42:43] op_sel_hi:[0,1]
	v_pk_mul_f32 v[40:41], v[44:45], v[40:41]
	v_pk_mul_f32 v[42:43], v[46:47], v[42:43]
	global_store_dwordx4 v[4:5], v[40:43], off offset:3072
	v_cmp_lt_i32_e32 vcc, s94, v0
	s_or_b64 s[2:3], vcc, s[2:3]
	v_lshl_add_u64 v[4:5], v[4:5], 0, s[12:13]
	s_andn2_b64 exec, exec, s[2:3]
	s_cbranch_execnz .LBB0_1633
	s_getpc_b64 s[98:99]
